# scan: the 4 workgroups of a head placed on one XCD (bx&7=head, bx>>3=column quarter) so they share L2 lines
# baseline (speedup 1.0000x reference)
.LBB0_369:
	s_or_b64 exec, exec, s[0:1]
	s_lshr_b32 s0, s50, 31
	s_add_i32 s0, s50, s0
	s_ashr_i32 s0, s0, 1
	v_writelane_b32 v248, s0, 4
	s_sub_i32 s0, s50, s0
	s_ashr_i32 s71, s50, 31
	s_lshl_b32 s31, s0, 3
	s_add_u32 s54, s78, 0x4200
	s_addc_u32 s55, s79, 0
	s_add_u32 s56, s78, 0x4400
	s_addc_u32 s57, s79, 0
	s_add_u32 s58, s78, 0x4500
	s_addc_u32 s59, s79, 0
	s_add_u32 s60, s78, 0x4600
	s_addc_u32 s61, s79, 0
	s_add_u32 s44, s78, 0x4700
	s_addc_u32 s45, s79, 0
	s_add_u32 s52, s78, 0x4800
	s_addc_u32 s53, s79, 0
	s_add_u32 s62, s78, 0x4900
	s_addc_u32 s63, s79, 0
	s_add_u32 s90, s78, 0x4a00
	s_addc_u32 s91, s79, 0
	s_add_u32 s92, s78, 0x4b00
	s_addc_u32 s93, s79, 0
	s_add_u32 s94, s78, 0x4c00
	s_addc_u32 s95, s79, 0
	s_add_u32 s96, s78, 0x4d00
	s_addc_u32 s97, s79, 0
	s_add_u32 s22, s78, 0x4e00
	s_addc_u32 s23, s79, 0
	s_add_u32 s64, s78, 0x4f00
	s_addc_u32 s65, s79, 0
	s_add_u32 s88, s78, 0x5000
	s_addc_u32 s89, s79, 0
	s_add_u32 s40, s78, 0x5100
	s_addc_u32 s41, s79, 0
	s_add_u32 s46, s78, 0x5200
	s_addc_u32 s47, s79, 0
	s_add_u32 s0, s78, 0x5300
	s_addc_u32 s1, s79, 0
	v_writelane_b32 v248, s0, 5
	s_cmp_eq_u32 s24, 15
	s_barrier
	v_writelane_b32 v248, s1, 6
	s_cselect_b64 s[0:1], -1, 0
	v_writelane_b32 v248, s0, 7
	s_cmp_eq_u32 s24, 14
	s_nop 0
	v_writelane_b32 v248, s1, 8
	s_cselect_b64 s[0:1], -1, 0
	v_writelane_b32 v248, s0, 9
	s_cmp_eq_u32 s24, 13
	s_mov_b32 s67, 0
	v_writelane_b32 v248, s1, 10
	s_cselect_b64 s[0:1], -1, 0
	v_writelane_b32 v248, s0, 11
	s_cmp_eq_u32 s24, 12
	v_mov_b32_e32 v161, 0
	v_writelane_b32 v248, s1, 12
	s_cselect_b64 s[0:1], -1, 0
	v_writelane_b32 v248, s0, 13
	s_cmp_eq_u32 s24, 11
	v_mov_b32_e32 v209, 1
	v_writelane_b32 v248, s1, 14
	s_cselect_b64 s[0:1], -1, 0
	v_writelane_b32 v248, s0, 15
	s_cmp_eq_u32 s24, 10
	v_mov_b32_e32 v162, 0x358637bd
	v_writelane_b32 v248, s1, 16
	s_cselect_b64 s[0:1], -1, 0
	v_writelane_b32 v248, s0, 17
	s_cmp_eq_u32 s24, 9
	v_mov_b32_e32 v210, 0x3ecc95a3
	v_writelane_b32 v248, s1, 18
	s_cselect_b64 s[0:1], -1, 0
	v_writelane_b32 v248, s0, 19
	s_cmp_eq_u32 s24, 8
	v_mov_b32_e32 v211, 0x17200000
	v_writelane_b32 v248, s1, 20
	s_cselect_b64 s[0:1], -1, 0
	v_writelane_b32 v248, s0, 21
	s_cmp_eq_u32 s24, 7
	v_mbcnt_hi_u32_b32 v208, -1, v10
	v_writelane_b32 v248, s1, 22
	s_cselect_b64 s[0:1], -1, 0
	v_writelane_b32 v248, s0, 23
	s_cmp_eq_u32 s24, 6
	v_mov_b32_e32 v212, 0x3000
	v_writelane_b32 v248, s1, 24
	s_cselect_b64 s[0:1], -1, 0
	v_writelane_b32 v248, s0, 25
	s_cmp_eq_u32 s24, 5
	v_mov_b32_e32 v213, 0x1800
	v_writelane_b32 v248, s1, 26
	s_cselect_b64 s[0:1], -1, 0
	v_writelane_b32 v248, s0, 27
	s_cmp_eq_u32 s24, 4
	v_mov_b32_e32 v214, 0x600000
	v_writelane_b32 v248, s1, 28
	s_cselect_b64 s[0:1], -1, 0
	v_writelane_b32 v248, s0, 29
	s_cmp_eq_u32 s24, 3
	v_mov_b32_e32 v215, 0x70
	v_writelane_b32 v248, s1, 30
	s_cselect_b64 s[0:1], -1, 0
	v_writelane_b32 v248, s0, 31
	s_cmp_eq_u32 s24, 2
	v_bfrev_b32_e32 v216, 0.5
	v_writelane_b32 v248, s1, 32
	s_cselect_b64 s[0:1], -1, 0
	v_writelane_b32 v248, s0, 33
	s_cmp_eq_u32 s24, 1
	v_mov_b32_e32 v217, 0xffffff00
	v_writelane_b32 v248, s1, 34
	s_cselect_b64 s[0:1], -1, 0
	v_writelane_b32 v248, s0, 35
	s_cmp_eq_u32 s24, 0
	v_mov_b32_e32 v164, 0x3f317218
	v_writelane_b32 v248, s1, 36
	s_cselect_b64 s[0:1], -1, 0
	v_writelane_b32 v248, s0, 37
	v_mov_b32_e32 v218, 0x7f800000
	v_mov_b32_e32 v219, 0x7fc00000
	v_writelane_b32 v248, s1, 38
	s_lshl_b32 s0, s24, 8
	s_add_u32 s0, s28, s0
	s_addc_u32 s1, s29, 0
	s_add_u32 s4, s0, 0x1400
	s_addc_u32 s5, s1, 0
	v_writelane_b32 v248, s4, 39
	s_add_u32 s0, s0, 0x2400
	s_addc_u32 s1, s1, 0
	v_writelane_b32 v248, s5, 40
	v_writelane_b32 v248, s0, 41
	v_mov_b32_e32 v220, 0xff800000
	v_mov_b32_e32 v221, 0x1c00
	v_writelane_b32 v248, s1, 42
	s_add_u32 s0, s78, 0x7400
	s_addc_u32 s1, s79, 0
	v_writelane_b32 v248, s0, 43
	s_mov_b32 s33, s50
	s_movk_i32 s6, 0x180
	v_writelane_b32 v248, s1, 44
	s_add_u32 s0, s78, 0x7500
	s_addc_u32 s1, s79, 0
	v_writelane_b32 v248, s0, 45
	s_cmpk_lt_i32 s2, 0x100
	s_mov_b32 s26, 0x800000
	v_writelane_b32 v248, s1, 46
	s_cselect_b64 s[0:1], -1, 0
	v_writelane_b32 v248, s0, 47
	s_and_b32 s0, s2, 7
	s_cmp_lt_u32 s0, 6
	s_cselect_b32 s0, s2, 32
	s_cmp_lt_u32 s0, 32
	s_movk_i32 s3, 0x3430
	v_writelane_b32 v248, s1, 48
	s_cselect_b64 s[0:1], -1, 0
	v_writelane_b32 v248, s0, 49
	s_ashr_i32 s35, s34, 31
	s_mov_b32 s27, 0xf149f2ca
	v_writelane_b32 v248, s1, 50
	s_abs_i32 s0, s50
	v_cvt_f32_u32_e32 v0, s0
	v_writelane_b32 v248, s0, 51
	s_sub_i32 s0, 0, s0
	s_mov_b32 s7, 0x41000000
	v_rcp_iflag_f32_e32 v0, v0
	s_mov_b64 s[68:69], 0x80
	s_mov_b32 s86, 0x3a800000
	s_mov_b64 s[74:75], 0x3600600
	v_mul_f32_e32 v0, 0x4f7ffffe, v0
	v_cvt_u32_f32_e32 v0, v0
	s_mov_b64 s[76:77], 0x6000
	s_mov_b32 s70, s67
	v_readfirstlane_b32 s1, v0
	s_mul_i32 s0, s0, s1
	s_mul_hi_u32 s0, s1, s0
	s_add_i32 s0, s1, s0
	v_writelane_b32 v248, s0, 52
	s_nop 0
	v_readlane_b32 s0, v248, 0
	v_readlane_b32 s1, v248, 1
	s_load_dword s0, s[0:1], 0x168
	s_mul_hi_i32 s1, s34, 0x180
	s_waitcnt lgkmcnt(0)
	s_mul_i32 s0, s51, s0
	s_mul_i32 s85, s0, s50
	s_mul_i32 s0, s34, 0x180
	v_writelane_b32 v248, s0, 53
	s_nop 1
	v_writelane_b32 v248, s1, 54
	s_lshl_b32 s0, s2, 6
	v_writelane_b32 v248, s0, 55
	s_lshl_b32 s0, s50, 6
	v_writelane_b32 v248, s0, 56
	s_add_i32 s0, 0, 0x23f00
	v_writelane_b32 v248, s0, 57
	s_add_i32 s0, 0, 0x23f04
	v_writelane_b32 v248, s0, 58
	s_lshl_b64 s[0:1], s[34:35], 10
	v_writelane_b32 v248, s0, 59
	s_nop 1
	v_writelane_b32 v248, s1, 60
	s_lshl_b64 s[0:1], s[34:35], 8
	v_writelane_b32 v248, s0, 61
	s_nop 1
	v_writelane_b32 v248, s1, 62
	s_lshl_b64 s[0:1], s[34:35], 9
	v_writelane_b32 v248, s0, 63
	s_nop 1
	v_writelane_b32 v247, s1, 0
	v_writelane_b32 v247, s34, 1
	s_mov_b32 s0, s50
	s_nop 0
	v_writelane_b32 v247, s35, 2
	v_writelane_b32 v247, s2, 3
	v_writelane_b32 v247, s0, 4
	s_nop 1
	v_writelane_b32 v247, s1, 5
	v_writelane_b32 v247, s31, 6
	v_writelane_b32 v247, s54, 7
	s_nop 1
	v_writelane_b32 v247, s55, 8
	v_writelane_b32 v247, s56, 9
	s_nop 1
	v_writelane_b32 v247, s57, 10
	v_writelane_b32 v247, s58, 11
	s_nop 1
	v_writelane_b32 v247, s59, 12
	v_writelane_b32 v247, s60, 13
	s_nop 1
	v_writelane_b32 v247, s61, 14
	v_writelane_b32 v247, s44, 15
	s_nop 1
	v_writelane_b32 v247, s45, 16
	v_writelane_b32 v247, s52, 17
	s_nop 1
	v_writelane_b32 v247, s53, 18
	v_writelane_b32 v247, s62, 19
	s_nop 1
	v_writelane_b32 v247, s63, 20
	v_writelane_b32 v247, s64, 21
	s_nop 1
	v_writelane_b32 v247, s65, 22
	v_writelane_b32 v247, s88, 23
	s_nop 1
	v_writelane_b32 v247, s89, 24
	v_writelane_b32 v247, s85, 25
	v_writelane_b32 v247, s22, 26
	s_nop 1
	v_writelane_b32 v247, s23, 27
	v_writelane_b32 v247, s40, 28
	s_nop 1
	v_writelane_b32 v247, s41, 29
	v_writelane_b32 v247, s46, 30
	s_nop 1
	v_writelane_b32 v247, s47, 31
	s_branch .LBB0_373

.LBB0_1822:
	s_or_b64 exec, exec, s[0:1]
	v_readlane_b32 s0, v248, 49
	v_readlane_b32 s1, v248, 50
	s_andn2_b64 vcc, exec, s[0:1]
	v_readlane_b32 s31, v247, 6
	s_waitcnt lgkmcnt(0)
	s_barrier
	s_cbranch_vccnz .LBB0_1853
	s_and_b32 s8, s2, 7
	s_lshl_b32 s8, s8, 2
	s_lshr_b32 s10, s2, 3
	s_or_b32 s10, s10, s8
	s_mov_b64 s[0:1], s[78:79]
	v_mov_b32_e32 v100, v163
	s_ashr_i32 s8, s10, 2
	v_readfirstlane_b32 s4, v100
	s_ashr_i32 s11, s4, 6
	v_and_b32_e32 v101, 63, v100
	s_cmp_gt_i32 s11, 1
	s_mov_b64 s[4:5], -1
	s_cbranch_scc0 .LBB0_1850
	s_add_u32 s16, s0, 0x14e00000
	s_addc_u32 s17, s1, 0
	s_add_u32 s4, s0, 0x13600000
	s_addc_u32 s5, s1, 0
	s_add_u32 s36, s0, 0x11e00000
	s_addc_u32 s37, s1, 0
	s_add_u32 s28, s0, 0x10600000
	s_addc_u32 s29, s1, 0
	s_min_u32 s38, s11, 57
	s_add_i32 s38, s38, -2
	s_ashr_i32 s9, s8, 31
	s_lshl_b32 s14, s38, 6
	s_lshl_b64 s[12:13], s[8:9], 8
	s_lshr_b32 s81, s38, 4
	s_and_b32 s14, s14, 0x3c0
	s_cmp_eq_u32 s81, 2
	s_cselect_b64 s[48:49], -1, 0
	v_or_b32_e32 v81, s14, v101
	s_and_b64 s[14:15], s[48:49], exec
	s_cselect_b32 s14, s5, s17
	s_cselect_b32 s15, s4, s16
	s_cmp_eq_u32 s81, 1
	s_cselect_b32 s15, s36, s15
	s_cselect_b32 s14, s37, s14
	s_cmp_lt_u32 s38, 16
	s_cselect_b32 s19, s29, s14
	s_cselect_b32 s18, s28, s15
	s_cmp_eq_u32 s81, 3
	s_cselect_b32 s14, 12, 13
	s_lshl_b64 s[20:21], s[12:13], s14
	s_lshl_b64 s[20:21], s[20:21], 1
	s_add_u32 s20, s18, s20
	s_addc_u32 s21, s19, s21
	s_min_u32 s15, s11, 51
	s_add_i32 s15, s15, 4
	s_lshr_b32 s82, s15, 4
	s_lshl_b32 s15, s15, 6
	s_and_b32 s15, s15, 0x3c0
	s_cmp_eq_u32 s82, 2
	v_lshlrev_b32_e32 v0, 4, v81
	s_cselect_b64 s[50:51], -1, 0
	global_load_dwordx4 v[36:39], v0, s[20:21]
	s_and_b64 s[20:21], s[50:51], exec
	v_or_b32_e32 v106, s15, v101
	s_cselect_b32 s15, s5, s17
	s_cselect_b32 s20, s4, s16
	s_cmp_eq_u32 s82, 1
	s_cselect_b32 s20, s36, s20
	s_cselect_b32 s15, s37, s15
	s_cmp_lt_u32 s11, 12
	s_cselect_b32 s21, s29, s15
	s_cselect_b32 s20, s28, s20
	s_cmp_eq_u32 s82, 3
	s_cselect_b32 s15, 12, 13
	s_lshl_b64 s[22:23], s[12:13], s15
	s_lshl_b64 s[22:23], s[22:23], 1
	s_add_u32 s22, s20, s22
	s_addc_u32 s23, s21, s23
	v_lshlrev_b32_e32 v0, 4, v106
	global_load_dwordx4 v[32:35], v0, s[22:23]
	s_min_u32 s22, s11, 45
	s_add_i32 s22, s22, 10
	s_lshr_b32 s83, s22, 4
	s_lshl_b32 s22, s22, 6
	s_and_b32 s22, s22, 0x3c0
	s_cmp_eq_u32 s83, 2
	s_cselect_b64 s[52:53], -1, 0
	v_or_b32_e32 v107, s22, v101
	s_and_b64 s[22:23], s[52:53], exec
	s_cselect_b32 s22, s5, s17
	s_cselect_b32 s23, s4, s16
	s_cmp_eq_u32 s83, 1
	s_cselect_b32 s30, s36, s23
	s_cselect_b32 s22, s37, s22
	s_cmp_lt_u32 s11, 6
	s_cselect_b32 s23, s29, s22
	s_cselect_b32 s22, s28, s30
	s_cmp_eq_u32 s83, 3
	s_cselect_b32 s66, 12, 13
	s_lshl_b64 s[28:29], s[12:13], s66
	s_lshl_b64 s[28:29], s[28:29], 1
	s_add_u32 s28, s22, s28
	s_addc_u32 s29, s23, s29
	v_lshlrev_b32_e32 v0, 4, v107
	global_load_dwordx4 v[28:31], v0, s[28:29]
	s_min_u32 s28, s11, 39
	s_add_i32 s28, s28, 16
	s_lshr_b32 s30, s28, 4
	s_lshl_b32 s28, s28, 6
	s_and_b32 s28, s28, 0x3c0
	s_cmp_eq_u32 s30, 2
	s_cselect_b64 s[54:55], -1, 0
	v_or_b32_e32 v115, s28, v101
	s_and_b64 s[28:29], s[54:55], exec
	s_cselect_b32 s28, s4, s16
	s_cselect_b32 s29, s5, s17
	s_cmp_eq_u32 s30, 1
	s_cselect_b32 s29, s37, s29
	s_cselect_b32 s28, s36, s28
	s_cmp_eq_u32 s30, 3
	s_cselect_b32 s72, 12, 13
	s_lshl_b64 s[30:31], s[12:13], s72
	s_lshl_b64 s[30:31], s[30:31], 1
	s_add_u32 s30, s28, s30
	s_addc_u32 s31, s29, s31
	v_lshlrev_b32_e32 v0, 4, v115
	global_load_dwordx4 v[20:23], v0, s[30:31]
	s_min_u32 s30, s11, 33
	s_add_i32 s30, s30, 22
	s_lshr_b32 s34, s30, 4
	s_lshl_b32 s30, s30, 6
	s_and_b32 s30, s30, 0x3c0
	s_cmp_eq_u32 s34, 2
	s_cselect_b64 s[62:63], -1, 0
	v_or_b32_e32 v117, s30, v101
	s_and_b64 s[30:31], s[62:63], exec
	s_cselect_b32 s30, s4, s16
	s_cselect_b32 s31, s5, s17
	s_cmp_eq_u32 s34, 1
	s_cselect_b32 s31, s37, s31
	s_cselect_b32 s30, s36, s30
	s_cmp_eq_u32 s34, 3
	s_cselect_b32 s73, 12, 13
	s_lshl_b64 s[34:35], s[12:13], s73
	s_lshl_b64 s[34:35], s[34:35], 1
	s_add_u32 s34, s30, s34
	s_addc_u32 s35, s31, s35
	v_lshlrev_b32_e32 v0, 4, v117
	global_load_dwordx4 v[0:3], v0, s[34:35]
	s_min_u32 s34, s11, 27
	s_add_i32 s34, s34, 28
	s_lshr_b32 s39, s34, 4
	s_lshl_b32 s34, s34, 6
	s_and_b32 s34, s34, 0x3c0
	s_cmp_eq_u32 s39, 2
	s_cselect_b64 s[56:57], -1, 0
	v_or_b32_e32 v80, s34, v101
	s_and_b64 s[34:35], s[56:57], exec
	s_cselect_b32 s34, s4, s16
	s_cselect_b32 s35, s5, s17
	s_cmp_eq_u32 s39, 1
	s_cselect_b32 s35, s37, s35
	s_cselect_b32 s34, s36, s34
	s_cmp_eq_u32 s39, 3
	s_cselect_b32 s78, 12, 13
	s_lshl_b64 s[36:37], s[12:13], s78
	s_lshl_b64 s[36:37], s[36:37], 1
	s_add_u32 s36, s34, s36
	s_addc_u32 s37, s35, s37
	v_lshlrev_b32_e32 v4, 4, v80
	global_load_dwordx4 v[4:7], v4, s[36:37]
	s_min_u32 s36, s11, 21
	s_add_i32 s36, s36, 34
	s_lshr_b32 s39, s36, 4
	s_lshl_b32 s36, s36, 6
	s_and_b32 s36, s36, 0x3c0
	s_cmp_eq_u32 s39, 2
	s_cselect_b64 s[58:59], -1, 0
	v_or_b32_e32 v40, s36, v101
	s_and_b64 s[36:37], s[58:59], exec
	s_cselect_b32 s37, s5, s17
	s_cselect_b32 s36, s4, s16
	s_cmp_eq_u32 s39, 3
	s_cselect_b32 s79, 12, 13
	s_lshl_b64 s[40:41], s[12:13], s79
	s_lshl_b64 s[40:41], s[40:41], 1
	s_add_u32 s40, s36, s40
	s_addc_u32 s41, s37, s41
	s_min_u32 s39, s11, 15
	s_add_i32 s39, s39, 40
	s_lshr_b32 s42, s39, 4
	s_lshl_b32 s39, s39, 6
	s_and_b32 s39, s39, 0x3c0
	s_cmp_eq_u32 s42, 2
	v_lshlrev_b32_e32 v8, 4, v40
	s_cselect_b64 s[60:61], -1, 0
	global_load_dwordx4 v[8:11], v8, s[40:41]
	s_and_b64 s[40:41], s[60:61], exec
	s_cselect_b32 s47, s5, s17
	s_cselect_b32 s46, s4, s16
	s_cmp_eq_u32 s42, 3
	s_cselect_b32 s80, 12, 13
	s_lshl_b64 s[4:5], s[12:13], s80
	s_lshl_b64 s[4:5], s[4:5], 1
	v_or_b32_e32 v41, s39, v101
	s_add_u32 s4, s46, s4
	s_addc_u32 s5, s47, s5
	v_lshlrev_b32_e32 v12, 4, v41
	global_load_dwordx4 v[12:15], v12, s[4:5]
	s_min_u32 s4, s11, 9
	s_lshl_b32 s4, s4, 6
	s_addk_i32 s4, 0x380
	s_and_b32 s4, s4, 0x3c0
	v_or_b32_e32 v42, s4, v101
	s_lshl_b64 s[4:5], s[8:9], 21
	s_add_u32 s4, s16, s4
	s_addc_u32 s5, s17, s5
	s_min_u32 s9, s11, 3
	v_lshl_or_b32 v17, s9, 6, v101
	v_or_b32_e32 v43, 0x100, v17
	v_lshlrev_b32_e32 v16, 4, v42
	v_lshlrev_b32_e32 v17, 4, v43
	global_load_dwordx4 v[24:27], v16, s[4:5]
	s_nop 0
	global_load_dwordx4 v[16:19], v17, s[4:5]
	s_cmp_lt_u32 s38, 32
	s_cselect_b64 s[4:5], -1, 0
	s_cmp_gt_u32 s38, 31
	s_mov_b64 s[38:39], -1
	s_mov_b32 s2, 0xc000
	s_cbranch_scc0 .LBB0_1826
	s_and_b64 s[38:39], s[48:49], exec
	s_cselect_b32 s9, 0x8000, s2
	s_mov_b64 s[38:39], 0
